# local barriers poll the XCC counter with a returning atomic add 0 (L2) instead of an sc1 load, on stack16
# speedup vs baseline: 1.0080x; 1.0041x over previous
; __device__ __forceinline__ unsigned xb_ld(unsigned* p)              { return __hip_atomic_load(p, __ATOMIC_RELAXED, __HIP_MEMORY_SCOPE_AGENT); }
; #define XB_SPIN(cond, bar) do { unsigned _sp = 0; while (cond) { __builtin_amdgcn_s_sleep(1); \
;     if ((++_sp & 255u) == 0u) { if (xb_ld(&(bar)[XB_TMO])) break; if (_sp > XB_SPIN_CAP) { atomicAdd(&(bar)[XB_TMO], 1u); break; } } } } while (0)
; __device__ __forceinline__ void xcd_barrier(const XcdBarrier& b) {
;     ...
;             else XB_SPIN(xb_ld(&bar[XB_TOPGEN]) == tg, bar);
;             __builtin_amdgcn_fence(__ATOMIC_ACQUIRE, "agent");
;             asm volatile("s_waitcnt vmcnt(0)" ::: "memory");
;         } else {
;             XB_SPIN(xb_ld(&bar[XB_TOPGEN]) == gen, bar);
;             __builtin_amdgcn_fence(__ATOMIC_ACQUIRE, "agent");
;             asm volatile("s_waitcnt vmcnt(0)" ::: "memory");
.Lxb_b2_lspin:
	global_atomic_add v5, v177, v177, s[4:5] sc0
	s_waitcnt vmcnt(0)
	v_cmp_ge_u32_e32 vcc, v5, v2
	s_cbranch_vccnz .Lxb_b2_done
	s_sleep 1
	s_add_i32 s100, s100, 1
	s_cmp_lt_u32 s100, 0x40000
	s_cbranch_scc1 .Lxb_b2_lspin
	s_branch .Lxb_b2_done
